# P10 top-k: sortable key built with 3 VALU per candidate (bfe sign mask, one bitop3, lshl_add with SALU-formed index) instead of 7
# baseline (speedup 1.0000x reference)
; DI void topk_half(const _Float16* __restrict__ sp, unsigned (&R)[16]) {
;     ...
;   for (int gi = 0; gi < 8; ++gi) {
;     unsigned Gk[16];
; #pragma unroll
;     for (int e = 0; e < 16; ++e) {
;       const int n = gi * 16 + e;
;       const unsigned bits = __builtin_bit_cast(unsigned short, sp[(long)n * NTOK]);
;       const unsigned o = (bits & 0x8000u) ? (~bits & 0xffffu) : (bits | 0x8000u);
;       Gk[e] = (o << 16) | (unsigned)(127 - n);
;     }
;     SORT16(Gk)
;     MERGE16(R, Gk)
.LBB0_1184:
	s_waitcnt vmcnt(0)
	ds_write_b128 v100, v[90:93]
	ds_write_b128 v100, v[94:97] offset:1024
	s_waitcnt lgkmcnt(0)
	global_load_dwordx4 v[90:93], v86, s[40:41]
	v_add_u32_e32 v87, 0x80000, v86
	global_load_dwordx4 v[94:97], v87, s[40:41]
	v_add_u32_e32 v86, 0x100000, v86
	ds_read_u16 v42, v101
	ds_read_u16 v47, v101 offset:128
	ds_read_u16 v46, v101 offset:256
	ds_read_u16 v45, v101 offset:384
	ds_read_u16 v44, v101 offset:512
	ds_read_u16 v43, v101 offset:640
	ds_read_u16 v17, v101 offset:768
	ds_read_u16 v16, v101 offset:896
	ds_read_u16 v14, v101 offset:1024
	ds_read_u16 v13, v101 offset:1152
	ds_read_u16 v12, v101 offset:1280
	ds_read_u16 v11, v101 offset:1408
	ds_read_u16 v10, v101 offset:1536
	ds_read_u16 v9, v101 offset:1664
	ds_read_u16 v8, v101 offset:1792
	ds_read_u16 v15, v101 offset:1920
	s_waitcnt lgkmcnt(0)
	s_mov_b32 s19, 0x8000
	s_add_i32 s0, s91, 15
	s_add_i32 s1, s91, 14
	s_add_i32 s6, s91, 13
	s_add_i32 s7, s91, 12
	s_add_i32 s8, s91, 11
	s_add_i32 s9, s91, 10
	s_add_i32 s10, s91, 9
	s_add_i32 s11, s91, 8
	s_add_i32 s12, s91, 7
	s_add_i32 s13, s91, 6
	s_add_i32 s14, s91, 5
	s_add_i32 s15, s91, 4
	s_add_i32 s16, s91, 3
	s_add_i32 s17, s91, 2
	s_add_i32 s18, s91, 1
	v_bfe_i32 v48, v42, 15, 1
	v_bitop3_b32 v42, v42, v48, s19 bitop3:0x1e
	v_bfe_i32 v49, v47, 15, 1
	v_bitop3_b32 v47, v47, v49, s19 bitop3:0x1e
	v_bfe_i32 v50, v46, 15, 1
	v_bitop3_b32 v46, v46, v50, s19 bitop3:0x1e
	v_bfe_i32 v51, v45, 15, 1
	v_bitop3_b32 v45, v45, v51, s19 bitop3:0x1e
	v_bfe_i32 v48, v44, 15, 1
	v_bitop3_b32 v44, v44, v48, s19 bitop3:0x1e
	v_bfe_i32 v49, v43, 15, 1
	v_bitop3_b32 v43, v43, v49, s19 bitop3:0x1e
	v_bfe_i32 v50, v17, 15, 1
	v_bitop3_b32 v17, v17, v50, s19 bitop3:0x1e
	v_bfe_i32 v51, v16, 15, 1
	v_bitop3_b32 v16, v16, v51, s19 bitop3:0x1e
	v_bfe_i32 v48, v14, 15, 1
	v_bitop3_b32 v14, v14, v48, s19 bitop3:0x1e
	v_bfe_i32 v49, v13, 15, 1
	v_bitop3_b32 v13, v13, v49, s19 bitop3:0x1e
	v_bfe_i32 v50, v12, 15, 1
	v_bitop3_b32 v12, v12, v50, s19 bitop3:0x1e
	v_bfe_i32 v51, v11, 15, 1
	v_bitop3_b32 v11, v11, v51, s19 bitop3:0x1e
	v_bfe_i32 v48, v10, 15, 1
	v_bitop3_b32 v10, v10, v48, s19 bitop3:0x1e
	v_bfe_i32 v49, v9, 15, 1
	v_bitop3_b32 v9, v9, v49, s19 bitop3:0x1e
	v_bfe_i32 v50, v8, 15, 1
	v_bitop3_b32 v8, v8, v50, s19 bitop3:0x1e
	v_bfe_i32 v51, v15, 15, 1
	v_bitop3_b32 v15, v15, v51, s19 bitop3:0x1e
	v_lshl_add_u32 v18, v47, 16, s1
	v_lshl_add_u32 v19, v46, 16, s6
	v_lshl_add_u32 v20, v45, 16, s7
	v_lshl_add_u32 v21, v44, 16, s8
	v_lshl_add_u32 v22, v43, 16, s9
	v_lshl_add_u32 v23, v17, 16, s10
	v_lshl_add_u32 v17, v16, 16, s11
	v_lshl_add_u32 v16, v14, 16, s12
	v_lshl_add_u32 v14, v13, 16, s13
	v_lshl_add_u32 v13, v12, 16, s14
	v_lshl_add_u32 v12, v11, 16, s15
	v_lshl_add_u32 v11, v10, 16, s16
	v_lshl_add_u32 v10, v9, 16, s17
	v_lshl_add_u32 v9, v8, 16, s18
	v_lshl_add_u32 v8, v15, 16, s91
	v_lshl_add_u32 v15, v42, 16, s0
	v_max_u32_e32 v42, v15, v18
	v_min_u32_e32 v15, v15, v18
	v_max_u32_e32 v18, v19, v20
	v_min_u32_e32 v19, v19, v20
	v_max_u32_e32 v20, v21, v22
	v_min_u32_e32 v21, v21, v22
	v_max_u32_e32 v22, v23, v17
	v_min_u32_e32 v17, v23, v17
	v_max_u32_e32 v23, v16, v14
	v_min_u32_e32 v14, v16, v14
	v_max_u32_e32 v16, v13, v12
	v_min_u32_e32 v12, v13, v12
	v_max_u32_e32 v13, v11, v10
	v_min_u32_e32 v10, v11, v10
	v_max_u32_e32 v11, v9, v8
	v_min_u32_e32 v8, v9, v8
	v_max_u32_e32 v9, v42, v18
	v_min_u32_e32 v18, v42, v18
	v_max_u32_e32 v42, v15, v19
	v_min_u32_e32 v15, v15, v19
	v_max_u32_e32 v19, v20, v22
	v_min_u32_e32 v20, v20, v22
	v_max_u32_e32 v22, v21, v17
	v_min_u32_e32 v17, v21, v17
	v_max_u32_e32 v21, v23, v16
	v_min_u32_e32 v16, v23, v16
	v_max_u32_e32 v23, v14, v12
	v_min_u32_e32 v12, v14, v12
	v_max_u32_e32 v14, v13, v11
	v_min_u32_e32 v11, v13, v11
	v_max_u32_e32 v13, v10, v8
	v_min_u32_e32 v8, v10, v8
	v_max_u32_e32 v10, v42, v18
	v_min_u32_e32 v18, v42, v18
	v_max_u32_e32 v42, v22, v20
	v_min_u32_e32 v20, v22, v20
	v_max_u32_e32 v22, v23, v16
	v_min_u32_e32 v16, v23, v16
	v_max_u32_e32 v23, v13, v11
	v_min_u32_e32 v11, v13, v11
	v_max_u32_e32 v13, v9, v19
	v_min_u32_e32 v9, v9, v19
	v_max_u32_e32 v19, v15, v17
	v_min_u32_e32 v15, v15, v17
	v_max_u32_e32 v17, v21, v14
	v_min_u32_e32 v14, v21, v14
	v_max_u32_e32 v21, v12, v8
	v_min_u32_e32 v8, v12, v8
	v_max_u32_e32 v12, v10, v42
	v_min_u32_e32 v10, v10, v42
	v_max_u32_e32 v42, v18, v20
	v_min_u32_e32 v18, v18, v20
	v_max_u32_e32 v20, v22, v23
	v_min_u32_e32 v22, v22, v23
	v_max_u32_e32 v23, v16, v11
	v_min_u32_e32 v11, v16, v11
	v_min_u32_e32 v16, v13, v17
	v_max_u32_e32 v43, v15, v8
	v_min_u32_e32 v8, v15, v8
	v_max3_u32 v13, v37, v13, v17
	v_max_u32_e32 v15, v42, v9
	v_min_u32_e32 v9, v42, v9
	v_max_u32_e32 v17, v19, v10
	v_min_u32_e32 v10, v19, v10
	v_max_u32_e32 v19, v23, v14
	v_min_u32_e32 v14, v23, v14
	v_max_u32_e32 v23, v21, v22
	v_min_u32_e32 v21, v21, v22
	v_max_u32_e32 v22, v12, v15
	v_min_u32_e32 v12, v12, v15
	v_max_u32_e32 v15, v17, v9
	v_min_u32_e32 v9, v17, v9
	v_max_u32_e32 v17, v10, v18
	v_min_u32_e32 v10, v10, v18
	v_max_u32_e32 v18, v20, v19
	v_min_u32_e32 v19, v20, v19
	v_max_u32_e32 v20, v23, v14
	v_min_u32_e32 v14, v23, v14
	v_max_u32_e32 v23, v21, v11
	v_min_u32_e32 v11, v21, v11
	v_max_u32_e32 v21, v22, v18
	v_min_u32_e32 v18, v22, v18
	v_max_u32_e32 v22, v12, v19
	v_min_u32_e32 v12, v12, v19
	v_max_u32_e32 v19, v15, v20
	v_min_u32_e32 v15, v15, v20
	v_max_u32_e32 v20, v9, v14
	v_min_u32_e32 v9, v9, v14
	v_max_u32_e32 v14, v17, v23
	v_min_u32_e32 v17, v17, v23
	v_max_u32_e32 v23, v10, v11
	v_min_u32_e32 v10, v10, v11
	v_max_u32_e32 v11, v20, v16
	v_min_u32_e32 v16, v20, v16
	v_max_u32_e32 v20, v14, v18
	v_min_u32_e32 v14, v14, v18
; DI void topk_half(const _Float16* __restrict__ sp, unsigned (&R)[16]) {
;     ...
;   for (int e = 0; e < 16; ++e) R[e] = 0u;
; #pragma unroll 1
;   for (int gi = 0; gi < 8; ++gi) {
;     unsigned Gk[16];
; #pragma unroll
;     for (int e = 0; e < 16; ++e) {
;       const int n = gi * 16 + e;
;       const unsigned bits = __builtin_bit_cast(unsigned short, sp[(long)n * NTOK]);
;       const unsigned o = (bits & 0x8000u) ? (~bits & 0xffffu) : (bits | 0x8000u);
;       Gk[e] = (o << 16) | (unsigned)(127 - n);
	v_max_u32_e32 v18, v23, v12
	v_min_u32_e32 v12, v23, v12
	v_max_u32_e32 v23, v43, v15
	v_min_u32_e32 v15, v43, v15
	v_max_u32_e32 v8, v35, v8
	v_max_u32_e32 v35, v22, v11
	v_min_u32_e32 v11, v22, v11
	v_max_u32_e32 v22, v19, v20
	v_min_u32_e32 v19, v19, v20
	v_max_u32_e32 v20, v18, v16
	v_min_u32_e32 v16, v18, v16
	v_max_u32_e32 v18, v23, v14
	v_min_u32_e32 v14, v23, v14
	v_max_u32_e32 v23, v12, v9
	v_min_u32_e32 v9, v12, v9
	v_max_u32_e32 v12, v15, v17
	v_min_u32_e32 v15, v15, v17
	v_min_u32_e32 v17, v21, v35
	v_min_u32_e32 v37, v22, v11
	v_min_u32_e32 v42, v19, v20
	v_min_u32_e32 v43, v18, v16
	v_min_u32_e32 v44, v14, v23
	v_min_u32_e32 v45, v12, v9
	v_min_u32_e32 v46, v15, v10
	v_max3_u32 v10, v40, v15, v10
	v_max3_u32 v9, v39, v12, v9
	v_max3_u32 v12, v38, v14, v23
	v_max3_u32 v14, v33, v18, v16
	v_max3_u32 v15, v31, v19, v20
	v_max3_u32 v3, v3, v22, v11
	v_max3_u32 v11, v34, v21, v35
	v_max_u32_e32 v16, v24, v46
	v_max_u32_e32 v18, v41, v45
	v_max_u32_e32 v19, v25, v44
	v_max_u32_e32 v20, v36, v43
	v_max_u32_e32 v21, v32, v42
	v_max_u32_e32 v22, v30, v37
	v_max_u32_e32 v1, v1, v17
	v_max_u32_e32 v17, v8, v14
	v_min_u32_e32 v8, v8, v14
	v_max_u32_e32 v14, v10, v15
	v_min_u32_e32 v10, v10, v15
	v_max_u32_e32 v15, v9, v3
	v_min_u32_e32 v3, v9, v3
	v_max_u32_e32 v9, v12, v11
	v_min_u32_e32 v11, v12, v11
	v_max_u32_e32 v12, v16, v21
	v_min_u32_e32 v16, v16, v21
	v_max_u32_e32 v21, v18, v22
	v_min_u32_e32 v18, v18, v22
	v_max_u32_e32 v22, v19, v1
	v_min_u32_e32 v1, v19, v1
	v_max_u32_e32 v19, v20, v13
	v_min_u32_e32 v13, v20, v13
	v_max_u32_e32 v20, v17, v15
	v_min_u32_e32 v15, v17, v15
	v_max_u32_e32 v17, v14, v9
	v_min_u32_e32 v9, v14, v9
	v_max_u32_e32 v14, v8, v3
	v_min_u32_e32 v3, v8, v3
	v_max_u32_e32 v8, v10, v11
	v_min_u32_e32 v10, v10, v11
	v_max_u32_e32 v11, v12, v22
	v_min_u32_e32 v12, v12, v22
	v_max_u32_e32 v22, v21, v19
	v_min_u32_e32 v19, v21, v19
	v_max_u32_e32 v21, v16, v1
	v_min_u32_e32 v1, v16, v1
	v_max_u32_e32 v16, v18, v13
	v_min_u32_e32 v13, v18, v13
	s_add_i32 s91, s91, -16
	v_max_u32_e32 v18, v20, v17
	v_min_u32_e32 v17, v20, v17
	v_max_u32_e32 v20, v15, v9
	v_min_u32_e32 v9, v15, v9
	v_max_u32_e32 v15, v14, v8
	v_min_u32_e32 v8, v14, v8
	v_max_u32_e32 v14, v3, v10
	v_min_u32_e32 v10, v3, v10
	v_max_u32_e32 v3, v11, v22
	v_min_u32_e32 v11, v11, v22
	v_max_u32_e32 v22, v12, v19
	v_min_u32_e32 v12, v12, v19
	v_max_u32_e32 v19, v21, v16
	v_min_u32_e32 v16, v21, v16
	v_max_u32_e32 v21, v1, v13
	v_min_u32_e32 v13, v1, v13
	s_cmp_lg_u32 s91, -16
	v_max_u32_e32 v35, v18, v3
	v_min_u32_e32 v24, v18, v3
	v_max_u32_e32 v40, v17, v11
	v_min_u32_e32 v41, v17, v11
	v_max_u32_e32 v39, v20, v22
	v_min_u32_e32 v25, v20, v22
	v_max_u32_e32 v38, v9, v12
	v_min_u32_e32 v36, v9, v12
	v_max_u32_e32 v33, v15, v19
	v_min_u32_e32 v32, v15, v19
	v_max_u32_e32 v31, v8, v16
	v_min_u32_e32 v30, v8, v16
	v_max_u32_e32 v3, v14, v21
	v_min_u32_e32 v1, v14, v21
	v_max_u32_e32 v34, v10, v13
	v_min_u32_e32 v37, v10, v13
	s_cbranch_scc1 .LBB0_1184
	v_lshl_add_u64 v[4:5], s[46:47], 0, v[4:5]
	v_mov_b32_e32 v55, 0
	s_movk_i32 s91, 0x70
	v_mov_b32_e32 v49, 0
	v_mov_b32_e32 v54, 0
	v_mov_b32_e32 v46, 0
	v_mov_b32_e32 v52, 0
	v_mov_b32_e32 v45, 0
	v_mov_b32_e32 v53, 0
	v_mov_b32_e32 v44, 0
	v_mov_b32_e32 v50, 0
	v_mov_b32_e32 v43, 0
	v_mov_b32_e32 v51, 0
	v_mov_b32_e32 v42, 0
	v_mov_b32_e32 v47, 0
	v_mov_b32_e32 v23, 0
	v_mov_b32_e32 v48, 0
	v_mov_b32_e32 v56, 0
.LBB0_1186:
	s_waitcnt vmcnt(0)
	ds_write_b128 v100, v[90:93]
	ds_write_b128 v100, v[94:97] offset:1024
	s_waitcnt lgkmcnt(0)
	global_load_dwordx4 v[90:93], v86, s[40:41]
	v_add_u32_e32 v87, 0x80000, v86
	global_load_dwordx4 v[94:97], v87, s[40:41]
	v_add_u32_e32 v86, 0x100000, v86
	ds_read_u16 v22, v101
	ds_read_u16 v61, v101 offset:128
	ds_read_u16 v60, v101 offset:256
	ds_read_u16 v59, v101 offset:384
	ds_read_u16 v58, v101 offset:512
	ds_read_u16 v57, v101 offset:640
	ds_read_u16 v15, v101 offset:768
	ds_read_u16 v14, v101 offset:896
	ds_read_u16 v12, v101 offset:1024
	ds_read_u16 v11, v101 offset:1152
	ds_read_u16 v10, v101 offset:1280
	ds_read_u16 v9, v101 offset:1408
	ds_read_u16 v8, v101 offset:1536
	ds_read_u16 v7, v101 offset:1664
	ds_read_u16 v6, v101 offset:1792
	ds_read_u16 v13, v101 offset:1920
	s_waitcnt lgkmcnt(0)
; DI void topk_half(const _Float16* __restrict__ sp, unsigned (&R)[16]) {
;     ...
;     for (int e = 0; e < 16; ++e) {
;       const int n = gi * 16 + e;
;       const unsigned bits = __builtin_bit_cast(unsigned short, sp[(long)n * NTOK]);
;       const unsigned o = (bits & 0x8000u) ? (~bits & 0xffffu) : (bits | 0x8000u);
;       Gk[e] = (o << 16) | (unsigned)(127 - n);
;     }
;     SORT16(Gk)
;     MERGE16(R, Gk)
	s_mov_b32 s19, 0x8000
	s_add_i32 s0, s91, 15
	s_add_i32 s1, s91, 14
	s_add_i32 s6, s91, 13
	s_add_i32 s7, s91, 12
	s_add_i32 s8, s91, 11
	s_add_i32 s9, s91, 10
	s_add_i32 s10, s91, 9
	s_add_i32 s11, s91, 8
	s_add_i32 s12, s91, 7
	s_add_i32 s13, s91, 6
	s_add_i32 s14, s91, 5
	s_add_i32 s15, s91, 4
	s_add_i32 s16, s91, 3
	s_add_i32 s17, s91, 2
	s_add_i32 s18, s91, 1
	v_bfe_i32 v62, v22, 15, 1
	v_bitop3_b32 v22, v22, v62, s19 bitop3:0x1e
	v_bfe_i32 v63, v61, 15, 1
	v_bitop3_b32 v61, v61, v63, s19 bitop3:0x1e
	v_bfe_i32 v64, v60, 15, 1
	v_bitop3_b32 v60, v60, v64, s19 bitop3:0x1e
	v_bfe_i32 v65, v59, 15, 1
	v_bitop3_b32 v59, v59, v65, s19 bitop3:0x1e
	v_bfe_i32 v62, v58, 15, 1
	v_bitop3_b32 v58, v58, v62, s19 bitop3:0x1e
	v_bfe_i32 v63, v57, 15, 1
	v_bitop3_b32 v57, v57, v63, s19 bitop3:0x1e
	v_bfe_i32 v64, v15, 15, 1
	v_bitop3_b32 v15, v15, v64, s19 bitop3:0x1e
	v_bfe_i32 v65, v14, 15, 1
	v_bitop3_b32 v14, v14, v65, s19 bitop3:0x1e
	v_bfe_i32 v62, v12, 15, 1
	v_bitop3_b32 v12, v12, v62, s19 bitop3:0x1e
	v_bfe_i32 v63, v11, 15, 1
	v_bitop3_b32 v11, v11, v63, s19 bitop3:0x1e
	v_bfe_i32 v64, v10, 15, 1
	v_bitop3_b32 v10, v10, v64, s19 bitop3:0x1e
	v_bfe_i32 v65, v9, 15, 1
	v_bitop3_b32 v9, v9, v65, s19 bitop3:0x1e
	v_bfe_i32 v62, v8, 15, 1
	v_bitop3_b32 v8, v8, v62, s19 bitop3:0x1e
	v_bfe_i32 v63, v7, 15, 1
	v_bitop3_b32 v7, v7, v63, s19 bitop3:0x1e
	v_bfe_i32 v64, v6, 15, 1
	v_bitop3_b32 v6, v6, v64, s19 bitop3:0x1e
	v_bfe_i32 v65, v13, 15, 1
	v_bitop3_b32 v13, v13, v65, s19 bitop3:0x1e
	v_lshl_add_u32 v16, v61, 16, s1
	v_lshl_add_u32 v17, v60, 16, s6
	v_lshl_add_u32 v18, v59, 16, s7
	v_lshl_add_u32 v19, v58, 16, s8
	v_lshl_add_u32 v20, v57, 16, s9
	v_lshl_add_u32 v21, v15, 16, s10
	v_lshl_add_u32 v15, v14, 16, s11
	v_lshl_add_u32 v14, v12, 16, s12
	v_lshl_add_u32 v12, v11, 16, s13
	v_lshl_add_u32 v11, v10, 16, s14
	v_lshl_add_u32 v10, v9, 16, s15
	v_lshl_add_u32 v9, v8, 16, s16
	v_lshl_add_u32 v8, v7, 16, s17
	v_lshl_add_u32 v7, v6, 16, s18
	v_lshl_add_u32 v6, v13, 16, s91
	v_lshl_add_u32 v13, v22, 16, s0
	v_max_u32_e32 v22, v13, v16
	v_min_u32_e32 v13, v13, v16
	v_max_u32_e32 v16, v17, v18
	v_min_u32_e32 v17, v17, v18
	v_max_u32_e32 v18, v19, v20
	v_min_u32_e32 v19, v19, v20
	v_max_u32_e32 v20, v21, v15
	v_min_u32_e32 v15, v21, v15
	v_max_u32_e32 v21, v14, v12
	v_min_u32_e32 v12, v14, v12
	v_max_u32_e32 v14, v11, v10
	v_min_u32_e32 v10, v11, v10
	v_max_u32_e32 v11, v9, v8
	v_min_u32_e32 v8, v9, v8
	v_max_u32_e32 v9, v7, v6
	v_min_u32_e32 v6, v7, v6
	v_max_u32_e32 v7, v22, v16
	v_min_u32_e32 v16, v22, v16
	v_max_u32_e32 v22, v13, v17
	v_min_u32_e32 v13, v13, v17
	v_max_u32_e32 v17, v18, v20
	v_min_u32_e32 v18, v18, v20
	v_max_u32_e32 v20, v19, v15
	v_min_u32_e32 v15, v19, v15
	v_max_u32_e32 v19, v21, v14
	v_min_u32_e32 v14, v21, v14
	v_max_u32_e32 v21, v12, v10
	v_min_u32_e32 v10, v12, v10
	v_max_u32_e32 v12, v11, v9
	v_min_u32_e32 v9, v11, v9
	v_max_u32_e32 v11, v8, v6
	v_min_u32_e32 v6, v8, v6
	v_max_u32_e32 v8, v22, v16
	v_min_u32_e32 v16, v22, v16
	v_max_u32_e32 v22, v20, v18
	v_min_u32_e32 v18, v20, v18
	v_max_u32_e32 v20, v21, v14
	v_min_u32_e32 v14, v21, v14
	v_max_u32_e32 v21, v11, v9
	v_min_u32_e32 v9, v11, v9
	v_max_u32_e32 v11, v7, v17
	v_min_u32_e32 v7, v7, v17
	v_max_u32_e32 v17, v13, v15
	v_min_u32_e32 v13, v13, v15
	v_max_u32_e32 v15, v19, v12
	v_min_u32_e32 v12, v19, v12
	v_max_u32_e32 v19, v10, v6
	v_min_u32_e32 v6, v10, v6
	v_max_u32_e32 v10, v8, v22
	v_min_u32_e32 v8, v8, v22
	v_max_u32_e32 v22, v16, v18
	v_min_u32_e32 v16, v16, v18
	v_max_u32_e32 v18, v20, v21
	v_min_u32_e32 v20, v20, v21
	v_max_u32_e32 v21, v14, v9
	v_min_u32_e32 v9, v14, v9
	v_min_u32_e32 v14, v11, v15
	v_max_u32_e32 v57, v13, v6
	v_min_u32_e32 v6, v13, v6
	v_max3_u32 v11, v56, v11, v15
	v_max_u32_e32 v13, v22, v7
	v_min_u32_e32 v7, v22, v7
	v_max_u32_e32 v15, v17, v8
	v_min_u32_e32 v8, v17, v8
	v_max_u32_e32 v17, v21, v12
	v_min_u32_e32 v12, v21, v12
	v_max_u32_e32 v21, v19, v20
	v_min_u32_e32 v19, v19, v20
	v_max_u32_e32 v20, v10, v13
	v_min_u32_e32 v10, v10, v13
	v_max_u32_e32 v13, v15, v7
	v_min_u32_e32 v7, v15, v7
	v_max_u32_e32 v15, v8, v16
	v_min_u32_e32 v8, v8, v16
	v_max_u32_e32 v16, v18, v17
	v_min_u32_e32 v17, v18, v17
	v_max_u32_e32 v18, v21, v12
	v_min_u32_e32 v12, v21, v12
	v_max_u32_e32 v21, v19, v9
	v_min_u32_e32 v9, v19, v9
	v_max_u32_e32 v19, v20, v16
	v_min_u32_e32 v16, v20, v16
	v_max_u32_e32 v20, v10, v17
	v_min_u32_e32 v10, v10, v17
	v_max_u32_e32 v17, v13, v18
	v_min_u32_e32 v13, v13, v18
	v_max_u32_e32 v18, v7, v12
	v_min_u32_e32 v7, v7, v12
	v_max_u32_e32 v12, v15, v21
	v_min_u32_e32 v15, v15, v21
	v_max_u32_e32 v21, v8, v9
	v_min_u32_e32 v8, v8, v9
	v_max_u32_e32 v9, v18, v14
	v_min_u32_e32 v14, v18, v14
	v_max_u32_e32 v18, v12, v16
	v_min_u32_e32 v12, v12, v16
	v_max_u32_e32 v16, v21, v10
	v_min_u32_e32 v10, v21, v10
	v_max_u32_e32 v21, v57, v13
	v_min_u32_e32 v13, v57, v13
	v_max_u32_e32 v22, v20, v9
	v_min_u32_e32 v9, v20, v9
	v_max_u32_e32 v20, v17, v18
	v_min_u32_e32 v17, v17, v18
	v_max_u32_e32 v18, v16, v14
	v_min_u32_e32 v14, v16, v14
	v_max_u32_e32 v16, v21, v12
	v_min_u32_e32 v12, v21, v12
	v_max_u32_e32 v21, v10, v7
	v_min_u32_e32 v7, v10, v7
	v_max_u32_e32 v10, v13, v15
	v_min_u32_e32 v13, v13, v15
	v_max_u32_e32 v6, v55, v6
	v_min_u32_e32 v15, v19, v22
	v_min_u32_e32 v55, v20, v9
	v_min_u32_e32 v56, v17, v18
	v_min_u32_e32 v57, v16, v14
	v_min_u32_e32 v58, v12, v21
	v_min_u32_e32 v59, v10, v7
	v_min_u32_e32 v60, v13, v8
	v_max3_u32 v8, v54, v13, v8
	v_max3_u32 v7, v52, v10, v7
	v_max3_u32 v10, v53, v12, v21
	v_max3_u32 v12, v50, v16, v14
	v_max3_u32 v13, v51, v17, v18
	v_max3_u32 v9, v47, v20, v9
; DI float key_val16(unsigned k) { const unsigned o = k >> 16; const unsigned short b = (unsigned short)((o & 0x8000u) ? (o & 0x7fffu) : (~o & 0xffffu)); return (float)__builtin_bit_cast(_Float16, b); }
; DI void phase10(const Params& P, char* smem) {
;     ...
;     float v1[16], v2[16]; unsigned W1[4] = {0u, 0u, 0u, 0u}, W2[4] = {0u, 0u, 0u, 0u};
; #pragma unroll
;     for (int k = 0; k < 16; ++k) {
;       v1[k] = key_val16(R1[k]); v2[k] = key_val16(R2[k]);
;       W1[k >> 2] |= (127u - (R1[k] & 127u)) << ((k & 3) * 8);
;       W2[k >> 2] |= (127u - (R2[k] & 127u)) << ((k & 3) * 8);
;     }
	v_max3_u32 v14, v48, v19, v22
	v_max_u32_e32 v16, v49, v60
	v_max_u32_e32 v17, v46, v59
	v_max_u32_e32 v18, v45, v58
	v_max_u32_e32 v19, v44, v57
	v_max_u32_e32 v20, v43, v56
	v_max_u32_e32 v21, v42, v55
	v_max_u32_e32 v15, v23, v15
	v_max_u32_e32 v22, v6, v12
	v_min_u32_e32 v6, v6, v12
	v_max_u32_e32 v12, v8, v13
	v_min_u32_e32 v8, v8, v13
	v_max_u32_e32 v13, v7, v9
	v_min_u32_e32 v7, v7, v9
	v_max_u32_e32 v9, v10, v14
	v_min_u32_e32 v10, v10, v14
	v_max_u32_e32 v14, v16, v20
	v_min_u32_e32 v16, v16, v20
	v_max_u32_e32 v20, v17, v21
	v_min_u32_e32 v17, v17, v21
	v_max_u32_e32 v21, v18, v15
	v_min_u32_e32 v15, v18, v15
	v_max_u32_e32 v18, v19, v11
	v_min_u32_e32 v11, v19, v11
	v_max_u32_e32 v19, v22, v13
	v_min_u32_e32 v13, v22, v13
	v_max_u32_e32 v22, v12, v9
	v_min_u32_e32 v9, v12, v9
	v_max_u32_e32 v12, v6, v7
	v_min_u32_e32 v6, v6, v7
	v_max_u32_e32 v7, v8, v10
	v_min_u32_e32 v8, v8, v10
	v_max_u32_e32 v10, v14, v21
	v_min_u32_e32 v14, v14, v21
	v_max_u32_e32 v21, v20, v18
	v_min_u32_e32 v18, v20, v18
	v_max_u32_e32 v20, v16, v15
	v_min_u32_e32 v15, v16, v15
	v_max_u32_e32 v16, v17, v11
	v_min_u32_e32 v11, v17, v11
	s_add_i32 s91, s91, -16
	v_max_u32_e32 v17, v19, v22
	v_min_u32_e32 v19, v19, v22
	v_max_u32_e32 v22, v13, v9
	v_min_u32_e32 v9, v13, v9
	v_max_u32_e32 v13, v12, v7
	v_min_u32_e32 v7, v12, v7
	v_max_u32_e32 v12, v6, v8
	v_min_u32_e32 v6, v6, v8
	v_max_u32_e32 v8, v10, v21
	v_min_u32_e32 v10, v10, v21
	v_max_u32_e32 v21, v14, v18
	v_min_u32_e32 v14, v14, v18
	v_max_u32_e32 v18, v20, v16
	v_min_u32_e32 v16, v20, v16
	v_max_u32_e32 v20, v15, v11
	v_min_u32_e32 v11, v15, v11
	s_cmp_lg_u32 s91, -16
	v_max_u32_e32 v55, v17, v8
	v_min_u32_e32 v49, v17, v8
	v_max_u32_e32 v54, v19, v10
	v_min_u32_e32 v46, v19, v10
	v_max_u32_e32 v52, v22, v21
	v_min_u32_e32 v45, v22, v21
	v_max_u32_e32 v53, v9, v14
	v_min_u32_e32 v44, v9, v14
	v_max_u32_e32 v50, v13, v18
	v_min_u32_e32 v43, v13, v18
	v_max_u32_e32 v51, v7, v16
	v_min_u32_e32 v42, v7, v16
	v_max_u32_e32 v47, v12, v20
	v_min_u32_e32 v23, v12, v20
	v_max_u32_e32 v48, v6, v11
	v_min_u32_e32 v56, v6, v11
	s_cbranch_scc1 .LBB0_1186
	v_lshlrev_b32_e32 v5, 8, v24
	v_lshlrev_b32_e32 v6, 16, v40
	v_and_b32_e32 v4, 0x7f, v35
	v_and_b32_e32 v5, 0x7f00, v5
	v_and_b32_e32 v6, 0x7f0000, v6
	v_or3_b32 v4, v5, v4, v6
	v_and_b32_sdwa v5, v46, s57 dst_sel:DWORD dst_unused:UNUSED_PAD src0_sel:WORD_1 src1_sel:DWORD
	v_xor_b32_sdwa v7, v46, v27 dst_sel:DWORD dst_unused:UNUSED_PAD src0_sel:WORD_1 src1_sel:DWORD
	v_cmp_gt_i32_e32 vcc, 0, v46
	v_and_b32_sdwa v6, v41, s57 dst_sel:DWORD dst_unused:UNUSED_PAD src0_sel:WORD_1 src1_sel:DWORD
	v_xor_b32_sdwa v8, v41, v27 dst_sel:DWORD dst_unused:UNUSED_PAD src0_sel:WORD_1 src1_sel:DWORD
	v_cndmask_b32_e32 v5, v7, v5, vcc
	v_cmp_gt_i32_e32 vcc, 0, v41
	v_xor_b32_sdwa v7, v39, v27 dst_sel:DWORD dst_unused:UNUSED_PAD src0_sel:WORD_1 src1_sel:DWORD
	v_xor_b32_sdwa v11, v36, v27 dst_sel:DWORD dst_unused:UNUSED_PAD src0_sel:WORD_1 src1_sel:DWORD
	v_cndmask_b32_e32 v6, v8, v6, vcc
	v_cvt_f32_f16_e32 v8, v5
	v_lshlrev_b32_e32 v5, 24, v41
	v_and_b32_e32 v5, 0x7f000000, v5
	v_cvt_f32_f16_e32 v12, v6
	v_bitop3_b32 v15, v4, s75, v5 bitop3:0x36
	v_and_b32_sdwa v4, v54, s57 dst_sel:DWORD dst_unused:UNUSED_PAD src0_sel:WORD_1 src1_sel:DWORD
	v_xor_b32_sdwa v6, v54, v27 dst_sel:DWORD dst_unused:UNUSED_PAD src0_sel:WORD_1 src1_sel:DWORD
	v_cmp_gt_i32_e32 vcc, 0, v54
	v_and_b32_sdwa v5, v39, s57 dst_sel:DWORD dst_unused:UNUSED_PAD src0_sel:WORD_1 src1_sel:DWORD
	v_xor_b32_sdwa v13, v24, v27 dst_sel:DWORD dst_unused:UNUSED_PAD src0_sel:WORD_1 src1_sel:DWORD
	v_cndmask_b32_e32 v4, v6, v4, vcc
	v_cmp_gt_i32_e32 vcc, 0, v39
	v_cvt_f32_f16_e32 v9, v4
	v_and_b32_sdwa v4, v52, s57 dst_sel:DWORD dst_unused:UNUSED_PAD src0_sel:WORD_1 src1_sel:DWORD
	v_cndmask_b32_e32 v5, v7, v5, vcc
	v_xor_b32_sdwa v6, v52, v27 dst_sel:DWORD dst_unused:UNUSED_PAD src0_sel:WORD_1 src1_sel:DWORD
	v_cmp_gt_i32_e32 vcc, 0, v52
	v_cvt_f32_f16_e32 v10, v5
	v_and_b32_sdwa v5, v40, s57 dst_sel:DWORD dst_unused:UNUSED_PAD src0_sel:WORD_1 src1_sel:DWORD
	v_xor_b32_sdwa v7, v40, v27 dst_sel:DWORD dst_unused:UNUSED_PAD src0_sel:WORD_1 src1_sel:DWORD
	v_cndmask_b32_e32 v4, v6, v4, vcc
	v_cmp_gt_i32_e32 vcc, 0, v40
	v_not_b32_sdwa v6, v25 dst_sel:DWORD dst_unused:UNUSED_PAD src0_sel:WORD_1
	v_cvt_f32_f16_e32 v21, v4
	v_cndmask_b32_e32 v5, v7, v5, vcc
	v_cvt_f32_f16_e32 v22, v5
	v_bfe_u32 v5, v25, 16, 15
	v_cmp_gt_i32_e32 vcc, 0, v25
	v_not_b32_sdwa v7, v38 dst_sel:DWORD dst_unused:UNUSED_PAD src0_sel:WORD_1
	v_and_b32_e32 v4, 0x7f, v39
	v_cndmask_b32_e32 v5, v6, v5, vcc
	v_cvt_f32_f16_e32 v14, v5
	v_bfe_u32 v5, v45, 16, 15
	v_not_b32_sdwa v6, v45 dst_sel:DWORD dst_unused:UNUSED_PAD src0_sel:WORD_1
	v_cmp_gt_i32_e32 vcc, 0, v45
	s_movk_i32 s0, 0xfe
	v_xor_b32_sdwa v57, v50, v27 dst_sel:DWORD dst_unused:UNUSED_PAD src0_sel:WORD_1 src1_sel:DWORD
	v_cndmask_b32_e32 v5, v6, v5, vcc
	v_bfe_u32 v6, v38, 16, 15
	v_cmp_gt_i32_e32 vcc, 0, v38
	v_cvt_f32_f16_e32 v20, v5
	v_lshlrev_b32_e32 v5, 8, v25
	v_cndmask_b32_e32 v6, v7, v6, vcc
	v_cvt_f32_f16_e32 v16, v6
	v_bfe_u32 v6, v53, 16, 15
	v_not_b32_sdwa v7, v53 dst_sel:DWORD dst_unused:UNUSED_PAD src0_sel:WORD_1
	v_cmp_gt_i32_e32 vcc, 0, v53
	v_and_b32_e32 v5, 0x7f00, v5
	v_xor_b32_sdwa v81, v32, v27 dst_sel:DWORD dst_unused:UNUSED_PAD src0_sel:WORD_1 src1_sel:DWORD
	v_cndmask_b32_e32 v6, v7, v6, vcc
	v_cvt_f32_f16_e32 v25, v6
	v_lshlrev_b32_e32 v6, 16, v38
	v_and_b32_e32 v6, 0x7f0000, v6
	v_or3_b32 v4, v5, v4, v6
	v_and_b32_sdwa v5, v49, s57 dst_sel:DWORD dst_unused:UNUSED_PAD src0_sel:WORD_1 src1_sel:DWORD
	v_xor_b32_sdwa v7, v49, v27 dst_sel:DWORD dst_unused:UNUSED_PAD src0_sel:WORD_1 src1_sel:DWORD
; DI float key_val16(unsigned k) { const unsigned o = k >> 16; const unsigned short b = (unsigned short)((o & 0x8000u) ? (o & 0x7fffu) : (~o & 0xffffu)); return (float)__builtin_bit_cast(_Float16, b); }
; DI unsigned candkey(float s, int pos) { const unsigned b = __float_as_uint(s); const unsigned o = (b >> 31) ? ~b : (b ^ 0x80000000u); return (o & 0xffffff00u) | (unsigned)(255 - pos); }
; DI void phase10(const Params& P, char* smem) {
;     ...
; #pragma unroll
;     for (int k = 0; k < 16; ++k) {
;       v1[k] = key_val16(R1[k]); v2[k] = key_val16(R2[k]);
;       W1[k >> 2] |= (127u - (R1[k] & 127u)) << ((k & 3) * 8);
;       W2[k >> 2] |= (127u - (R2[k] & 127u)) << ((k & 3) * 8);
;     }
;     unsigned C0[16], C1[16], C2[16], C3[16];
;     C0[0] = candkey(v1[0] + v2[0], 0);
;     C0[1] = candkey(v1[0] + v2[1], 1);
;     C0[2] = candkey(v1[0] + v2[2], 2);
;     C0[3] = candkey(v1[0] + v2[3], 3);
;     C0[4] = candkey(v1[0] + v2[4], 4);
;     C0[5] = candkey(v1[0] + v2[5], 5);
;     C0[6] = candkey(v1[0] + v2[6], 6);
;     C0[7] = candkey(v1[0] + v2[7], 7);
;     C0[8] = candkey(v1[0] + v2[8], 8);
;     C0[9] = candkey(v1[0] + v2[9], 9);
;     C0[10] = candkey(v1[0] + v2[10], 10);
;     C0[11] = candkey(v1[0] + v2[11], 11);
;     C0[12] = candkey(v1[0] + v2[12], 12);
;     C0[13] = candkey(v1[0] + v2[13], 13);
;     C0[14] = candkey(v1[0] + v2[14], 14);
;     C0[15] = candkey(v1[0] + v2[15], 15);
;     C1[0] = candkey(v1[1] + v2[0], 16);
;     C1[1] = candkey(v1[1] + v2[1], 17);
;     C1[2] = candkey(v1[1] + v2[2], 18);
;     C1[3] = candkey(v1[1] + v2[3], 19);
;     C1[4] = candkey(v1[1] + v2[4], 20);
;     C1[5] = candkey(v1[1] + v2[5], 21);
;     C1[6] = candkey(v1[1] + v2[6], 22);
;     C1[7] = candkey(v1[1] + v2[7], 23);
;     C1[8] = candkey(v1[2] + v2[0], 32);
;     C1[9] = candkey(v1[2] + v2[1], 33);
;     C1[10] = candkey(v1[2] + v2[2], 34);
;     C1[11] = candkey(v1[2] + v2[3], 35);
;     C1[12] = candkey(v1[2] + v2[4], 36);
;     C1[13] = candkey(v1[3] + v2[0], 48);
;     C1[14] = candkey(v1[3] + v2[1], 49);
;     C1[15] = candkey(v1[3] + v2[2], 50);
	v_cmp_gt_i32_e32 vcc, 0, v49
	v_and_b32_sdwa v6, v36, s57 dst_sel:DWORD dst_unused:UNUSED_PAD src0_sel:WORD_1 src1_sel:DWORD
	v_xor_b32_sdwa v38, v35, v27 dst_sel:DWORD dst_unused:UNUSED_PAD src0_sel:WORD_1 src1_sel:DWORD
	v_cndmask_b32_e32 v5, v7, v5, vcc
	v_cmp_gt_i32_e32 vcc, 0, v36
	s_nop 1
	v_cndmask_b32_e32 v7, v11, v6, vcc
	v_cvt_f32_f16_e32 v18, v7
	v_and_b32_sdwa v7, v24, s57 dst_sel:DWORD dst_unused:UNUSED_PAD src0_sel:WORD_1 src1_sel:DWORD
	v_cmp_gt_i32_e32 vcc, 0, v24
	v_cvt_f32_f16_e32 v6, v5
	v_and_b32_sdwa v5, v44, s57 dst_sel:DWORD dst_unused:UNUSED_PAD src0_sel:WORD_1 src1_sel:DWORD
	v_xor_b32_sdwa v11, v44, v27 dst_sel:DWORD dst_unused:UNUSED_PAD src0_sel:WORD_1 src1_sel:DWORD
	v_cndmask_b32_e32 v7, v13, v7, vcc
	v_cmp_gt_i32_e32 vcc, 0, v44
	v_cvt_f32_f16_e32 v64, v7
	v_lshlrev_b32_e32 v7, 16, v31
	v_cndmask_b32_e32 v5, v11, v5, vcc
	v_cvt_f32_f16_e32 v24, v5
	v_lshlrev_b32_e32 v5, 24, v36
	v_and_b32_e32 v5, 0x7f000000, v5
	v_bitop3_b32 v17, v4, s75, v5 bitop3:0x36
	v_lshlrev_b32_e32 v5, 8, v32
	v_and_b32_e32 v4, 0x7f, v33
	v_and_b32_e32 v5, 0x7f00, v5
	v_and_b32_e32 v7, 0x7f0000, v7
	v_or3_b32 v4, v5, v4, v7
	v_lshlrev_b32_e32 v5, 24, v30
	v_and_b32_e32 v5, 0x7f000000, v5
	v_bitop3_b32 v19, v4, s75, v5 bitop3:0x36
	v_lshlrev_b32_e32 v5, 8, v1
	v_and_b32_e32 v11, 0x7f00, v5
	v_and_b32_sdwa v5, v55, s57 dst_sel:DWORD dst_unused:UNUSED_PAD src0_sel:WORD_1 src1_sel:DWORD
	v_xor_b32_sdwa v13, v55, v27 dst_sel:DWORD dst_unused:UNUSED_PAD src0_sel:WORD_1 src1_sel:DWORD
	v_cmp_gt_i32_e32 vcc, 0, v55
	v_and_b32_sdwa v7, v34, s57 dst_sel:DWORD dst_unused:UNUSED_PAD src0_sel:WORD_1 src1_sel:DWORD
	v_xor_b32_sdwa v36, v34, v27 dst_sel:DWORD dst_unused:UNUSED_PAD src0_sel:WORD_1 src1_sel:DWORD
	v_cndmask_b32_e32 v5, v13, v5, vcc
	v_cmp_gt_i32_e32 vcc, 0, v34
	v_and_b32_e32 v4, 0x7f, v3
	s_nop 0
	v_cndmask_b32_e32 v13, v36, v7, vcc
	v_cvt_f32_f16_e32 v7, v5
	v_cvt_f32_f16_e32 v5, v13
	v_bfe_u32 v13, v48, 16, 15
	v_not_b32_sdwa v36, v48 dst_sel:DWORD dst_unused:UNUSED_PAD src0_sel:WORD_1
	v_cmp_gt_i32_e32 vcc, 0, v48
	s_nop 1
	v_cndmask_b32_e32 v13, v36, v13, vcc
	v_cvt_f32_f16_e32 v67, v13
	v_lshlrev_b32_e32 v13, 16, v34
	v_and_b32_e32 v13, 0x7f0000, v13
	v_or3_b32 v11, v11, v4, v13
	v_bfe_u32 v4, v37, 16, 15
	v_not_b32_sdwa v13, v37 dst_sel:DWORD dst_unused:UNUSED_PAD src0_sel:WORD_1
	v_cmp_gt_i32_e32 vcc, 0, v37
	v_xor_b32_sdwa v36, v56, v27 dst_sel:DWORD dst_unused:UNUSED_PAD src0_sel:WORD_1 src1_sel:DWORD
	v_and_b32_sdwa v34, v35, s57 dst_sel:DWORD dst_unused:UNUSED_PAD src0_sel:WORD_1 src1_sel:DWORD
	v_cndmask_b32_e32 v4, v13, v4, vcc
	v_and_b32_sdwa v13, v56, s57 dst_sel:DWORD dst_unused:UNUSED_PAD src0_sel:WORD_1 src1_sel:DWORD
	v_cmp_gt_i32_e32 vcc, 0, v56
	v_cvt_f32_f16_e32 v4, v4
	s_nop 0
	v_cndmask_b32_e32 v13, v36, v13, vcc
	v_cmp_gt_i32_e32 vcc, 0, v35
	v_cvt_f32_f16_e32 v66, v13
	v_lshlrev_b32_e32 v13, 24, v37
	v_cndmask_b32_e32 v34, v38, v34, vcc
	v_cvt_f32_f16_e32 v68, v34
	v_and_b32_e32 v13, 0x7f000000, v13
	v_bitop3_b32 v34, v11, s75, v13 bitop3:0x36
	v_pk_add_f32 v[36:37], v[68:69], v[6:7] op_sel_hi:[0,1]
	v_cmp_lt_i32_e32 vcc, -1, v37
	v_pk_add_f32 v[38:39], v[68:69], v[8:9] op_sel_hi:[0,1]
	v_and_b32_e32 v13, 0xffffff00, v36
	v_cndmask_b32_e32 v11, v28, v29, vcc
	v_cmp_lt_i32_e32 vcc, -1, v36
	v_bitop3_b32 v35, v11, s3, v37 bitop3:0xde
	v_pk_add_f32 v[40:41], v[68:69], v[20:21] op_sel_hi:[0,1]
	v_cndmask_b32_e32 v11, v28, v29, vcc
	v_cmp_lt_i32_e32 vcc, -1, v39
	v_bitop3_b32 v36, v11, s0, v13 bitop3:0xde
	v_and_b32_e32 v13, 0xffffff00, v39
	v_cndmask_b32_e32 v11, v28, v29, vcc
	s_movk_i32 s0, 0xfd
	v_cmp_lt_i32_e32 vcc, -1, v38
	v_bitop3_b32 v37, v11, s0, v13 bitop3:0xde
	v_and_b32_e32 v13, 0xffffff00, v38
	v_cndmask_b32_e32 v11, v28, v29, vcc
	s_movk_i32 s0, 0xfc
	v_cmp_lt_i32_e32 vcc, -1, v41
	v_bitop3_b32 v38, v11, s0, v13 bitop3:0xde
	v_and_b32_e32 v13, 0xffffff00, v41
	v_cndmask_b32_e32 v11, v28, v29, vcc
	s_movk_i32 s0, 0xfb
	v_cmp_lt_i32_e32 vcc, -1, v40
	v_pk_add_f32 v[58:59], v[68:69], v[24:25] op_sel_hi:[0,1]
	v_bitop3_b32 v39, v11, s0, v13 bitop3:0xde
	v_cndmask_b32_e32 v11, v28, v29, vcc
	v_and_b32_e32 v13, 0xffffff00, v40
	s_movk_i32 s0, 0xfa
	v_cmp_lt_i32_e32 vcc, -1, v59
	v_bitop3_b32 v40, v11, s0, v13 bitop3:0xde
	v_and_b32_e32 v13, 0xffffff00, v59
	v_cndmask_b32_e32 v11, v28, v29, vcc
	s_movk_i32 s0, 0xf9
	v_bitop3_b32 v41, v11, s0, v13 bitop3:0xde
	v_and_b32_sdwa v11, v50, s57 dst_sel:DWORD dst_unused:UNUSED_PAD src0_sel:WORD_1 src1_sel:DWORD
	v_cmp_gt_i32_e32 vcc, 0, v50
	v_and_b32_sdwa v13, v43, s57 dst_sel:DWORD dst_unused:UNUSED_PAD src0_sel:WORD_1 src1_sel:DWORD
	v_xor_b32_sdwa v59, v43, v27 dst_sel:DWORD dst_unused:UNUSED_PAD src0_sel:WORD_1 src1_sel:DWORD
	v_cndmask_b32_e32 v11, v57, v11, vcc
	v_cmp_gt_i32_e32 vcc, 0, v43
	v_cvt_f32_f16_e32 v61, v11
	s_movk_i32 s0, 0xf8
	v_cndmask_b32_e32 v13, v59, v13, vcc
	v_cvt_f32_f16_e32 v60, v13
	v_cmp_lt_i32_e32 vcc, -1, v58
	v_and_b32_e32 v13, 0xffffff00, v58
	v_xor_b32_sdwa v59, v51, v27 dst_sel:DWORD dst_unused:UNUSED_PAD src0_sel:WORD_1 src1_sel:DWORD
	v_pk_add_f32 v[60:61], v[68:69], v[60:61] op_sel_hi:[0,1]
	v_cndmask_b32_e32 v11, v28, v29, vcc
	v_cmp_lt_i32_e32 vcc, -1, v61
	v_bitop3_b32 v57, v11, s0, v13 bitop3:0xde
	v_and_b32_e32 v13, 0xffffff00, v61
	v_cndmask_b32_e32 v11, v28, v29, vcc
	s_movk_i32 s0, 0xf7
	v_bitop3_b32 v58, v11, s0, v13 bitop3:0xde
	v_and_b32_sdwa v11, v51, s57 dst_sel:DWORD dst_unused:UNUSED_PAD src0_sel:WORD_1 src1_sel:DWORD
	v_cmp_gt_i32_e32 vcc, 0, v51
	v_and_b32_sdwa v13, v42, s57 dst_sel:DWORD dst_unused:UNUSED_PAD src0_sel:WORD_1 src1_sel:DWORD
	v_xor_b32_sdwa v61, v42, v27 dst_sel:DWORD dst_unused:UNUSED_PAD src0_sel:WORD_1 src1_sel:DWORD
; DI unsigned candkey(float s, int pos) { const unsigned b = __float_as_uint(s); const unsigned o = (b >> 31) ? ~b : (b ^ 0x80000000u); return (o & 0xffffff00u) | (unsigned)(255 - pos); }
; DI void phase10(const Params& P, char* smem) {
;     ...
;     C0[0] = candkey(v1[0] + v2[0], 0);
;     C0[1] = candkey(v1[0] + v2[1], 1);
;     C0[2] = candkey(v1[0] + v2[2], 2);
;     C0[3] = candkey(v1[0] + v2[3], 3);
;     C0[4] = candkey(v1[0] + v2[4], 4);
;     C0[5] = candkey(v1[0] + v2[5], 5);
;     C0[6] = candkey(v1[0] + v2[6], 6);
;     C0[7] = candkey(v1[0] + v2[7], 7);
;     C0[8] = candkey(v1[0] + v2[8], 8);
;     C0[9] = candkey(v1[0] + v2[9], 9);
;     C0[10] = candkey(v1[0] + v2[10], 10);
;     C0[11] = candkey(v1[0] + v2[11], 11);
;     C0[12] = candkey(v1[0] + v2[12], 12);
;     C0[13] = candkey(v1[0] + v2[13], 13);
;     C0[14] = candkey(v1[0] + v2[14], 14);
;     C0[15] = candkey(v1[0] + v2[15], 15);
;     C1[0] = candkey(v1[1] + v2[0], 16);
;     C1[1] = candkey(v1[1] + v2[1], 17);
;     C1[2] = candkey(v1[1] + v2[2], 18);
;     C1[3] = candkey(v1[1] + v2[3], 19);
;     C1[4] = candkey(v1[1] + v2[4], 20);
;     C1[5] = candkey(v1[1] + v2[5], 21);
;     C1[6] = candkey(v1[1] + v2[6], 22);
;     C1[7] = candkey(v1[1] + v2[7], 23);
;     C1[8] = candkey(v1[2] + v2[0], 32);
;     C1[9] = candkey(v1[2] + v2[1], 33);
;     C1[10] = candkey(v1[2] + v2[2], 34);
;     C1[11] = candkey(v1[2] + v2[3], 35);
;     C1[12] = candkey(v1[2] + v2[4], 36);
;     C1[13] = candkey(v1[3] + v2[0], 48);
;     C1[14] = candkey(v1[3] + v2[1], 49);
;     C1[15] = candkey(v1[3] + v2[2], 50);
;     C2[0] = candkey(v1[3] + v2[3], 51);
;     C2[1] = candkey(v1[4] + v2[0], 64);
;     C2[2] = candkey(v1[4] + v2[1], 65);
;     C2[3] = candkey(v1[4] + v2[2], 66);
;     C2[4] = candkey(v1[5] + v2[0], 80);
;     C2[5] = candkey(v1[5] + v2[1], 81);
;     C2[6] = candkey(v1[6] + v2[0], 96);
;     C2[7] = candkey(v1[6] + v2[1], 97);
;     C2[8] = candkey(v1[7] + v2[0], 112);
;     C2[9] = candkey(v1[7] + v2[1], 113);
;     C2[10] = candkey(v1[8] + v2[0], 128);
;     C2[11] = candkey(v1[9] + v2[0], 144);
;     C2[12] = candkey(v1[10] + v2[0], 160);
;     C2[13] = candkey(v1[11] + v2[0], 176);
;     C2[14] = candkey(v1[12] + v2[0], 192);
;     C2[15] = candkey(v1[13] + v2[0], 208);
;     C3[0] = candkey(v1[14] + v2[0], 224);
;     C3[1] = candkey(v1[15] + v2[0], 240);
	v_cndmask_b32_e32 v11, v59, v11, vcc
	v_cmp_gt_i32_e32 vcc, 0, v42
	v_cvt_f32_f16_e32 v63, v11
	s_movk_i32 s0, 0xf6
	v_cndmask_b32_e32 v13, v61, v13, vcc
	v_cvt_f32_f16_e32 v62, v13
	v_cmp_lt_i32_e32 vcc, -1, v60
	v_and_b32_e32 v13, 0xffffff00, v60
	v_xor_b32_sdwa v61, v47, v27 dst_sel:DWORD dst_unused:UNUSED_PAD src0_sel:WORD_1 src1_sel:DWORD
	v_pk_add_f32 v[62:63], v[68:69], v[62:63] op_sel_hi:[0,1]
	v_cndmask_b32_e32 v11, v28, v29, vcc
	v_cmp_lt_i32_e32 vcc, -1, v63
	v_bitop3_b32 v59, v11, s0, v13 bitop3:0xde
	v_and_b32_e32 v13, 0xffffff00, v63
	v_cndmask_b32_e32 v11, v28, v29, vcc
	s_movk_i32 s0, 0xf5
	v_bitop3_b32 v60, v11, s0, v13 bitop3:0xde
	v_and_b32_sdwa v11, v47, s57 dst_sel:DWORD dst_unused:UNUSED_PAD src0_sel:WORD_1 src1_sel:DWORD
	v_cmp_gt_i32_e32 vcc, 0, v47
	v_and_b32_sdwa v13, v23, s57 dst_sel:DWORD dst_unused:UNUSED_PAD src0_sel:WORD_1 src1_sel:DWORD
	v_xor_b32_sdwa v63, v23, v27 dst_sel:DWORD dst_unused:UNUSED_PAD src0_sel:WORD_1 src1_sel:DWORD
	v_cndmask_b32_e32 v11, v61, v11, vcc
	v_cmp_gt_i32_e32 vcc, 0, v23
	v_cvt_f32_f16_e32 v71, v11
	s_movk_i32 s0, 0xf4
	v_cndmask_b32_e32 v13, v63, v13, vcc
	v_cvt_f32_f16_e32 v70, v13
	v_cmp_lt_i32_e32 vcc, -1, v62
	v_and_b32_e32 v13, 0xffffff00, v62
	v_pk_add_f32 v[66:67], v[68:69], v[66:67] op_sel_hi:[0,1]
	v_pk_add_f32 v[70:71], v[68:69], v[70:71] op_sel_hi:[0,1]
	v_cndmask_b32_e32 v11, v28, v29, vcc
	v_cmp_lt_i32_e32 vcc, -1, v71
	v_bitop3_b32 v61, v11, s0, v13 bitop3:0xde
	v_and_b32_e32 v13, 0xffffff00, v71
	v_cndmask_b32_e32 v11, v28, v29, vcc
	s_movk_i32 s0, 0xf3
	v_cmp_lt_i32_e32 vcc, -1, v70
	v_bitop3_b32 v62, v11, s0, v13 bitop3:0xde
	v_and_b32_e32 v13, 0xffffff00, v70
	v_cndmask_b32_e32 v11, v28, v29, vcc
	s_movk_i32 s0, 0xf2
	v_cmp_lt_i32_e32 vcc, -1, v67
	v_bitop3_b32 v63, v11, s0, v13 bitop3:0xde
	v_and_b32_e32 v13, 0xffffff00, v67
	v_cndmask_b32_e32 v11, v28, v29, vcc
	s_movk_i32 s0, 0xf1
	v_bitop3_b32 v65, v11, s0, v13 bitop3:0xde
	v_cmp_lt_i32_e32 vcc, -1, v66
	v_and_b32_e32 v13, 0xffffff00, v66
	v_pk_add_f32 v[66:67], v[64:65], v[6:7] op_sel_hi:[0,1]
	v_cndmask_b32_e32 v11, v28, v29, vcc
	s_movk_i32 s0, 0xf0
	v_cmp_lt_i32_e32 vcc, -1, v67
	v_bitop3_b32 v68, v11, s0, v13 bitop3:0xde
	v_and_b32_e32 v13, 0xffffff00, v67
	v_cndmask_b32_e32 v11, v28, v29, vcc
	s_movk_i32 s0, 0xef
	v_bitop3_b32 v69, v11, s0, v13 bitop3:0xde
	v_cmp_lt_i32_e32 vcc, -1, v66
	v_and_b32_e32 v13, 0xffffff00, v66
	v_pk_add_f32 v[66:67], v[64:65], v[8:9] op_sel_hi:[0,1]
	v_cndmask_b32_e32 v11, v28, v29, vcc
	s_movk_i32 s0, 0xee
	v_cmp_lt_i32_e32 vcc, -1, v67
	v_bitop3_b32 v70, v11, s0, v13 bitop3:0xde
	v_and_b32_e32 v13, 0xffffff00, v67
	v_cndmask_b32_e32 v11, v28, v29, vcc
	s_movk_i32 s0, 0xed
	v_bitop3_b32 v71, v11, s0, v13 bitop3:0xde
	v_cmp_lt_i32_e32 vcc, -1, v66
	v_and_b32_e32 v13, 0xffffff00, v66
	v_pk_add_f32 v[66:67], v[64:65], v[20:21] op_sel_hi:[0,1]
	v_cndmask_b32_e32 v11, v28, v29, vcc
	s_movk_i32 s0, 0xec
	v_cmp_lt_i32_e32 vcc, -1, v67
	v_bitop3_b32 v72, v11, s0, v13 bitop3:0xde
	v_and_b32_e32 v13, 0xffffff00, v67
	v_cndmask_b32_e32 v11, v28, v29, vcc
	s_movk_i32 s0, 0xeb
	v_cmp_lt_i32_e32 vcc, -1, v66
	v_pk_add_f32 v[24:25], v[64:65], v[24:25] op_sel_hi:[0,1]
	v_bitop3_b32 v67, v11, s0, v13 bitop3:0xde
	v_cndmask_b32_e32 v11, v28, v29, vcc
	v_and_b32_e32 v13, 0xffffff00, v66
	s_movk_i32 s0, 0xea
	v_cmp_lt_i32_e32 vcc, -1, v25
	v_bitop3_b32 v66, v11, s0, v13 bitop3:0xde
	v_and_b32_e32 v13, 0xffffff00, v25
	v_cndmask_b32_e32 v11, v28, v29, vcc
	s_movk_i32 s0, 0xe9
	v_bitop3_b32 v64, v11, s0, v13 bitop3:0xde
	v_cmp_lt_i32_e32 vcc, -1, v24
	v_and_b32_e32 v13, 0xffffff00, v24
	v_pk_add_f32 v[24:25], v[22:23], v[6:7] op_sel_hi:[0,1]
	v_cndmask_b32_e32 v11, v28, v29, vcc
	v_cmp_lt_i32_e32 vcc, -1, v25
	v_bitop3_b32 v73, v11, s92, v13 bitop3:0xde
	v_and_b32_e32 v13, 0xffffff00, v25
	v_cndmask_b32_e32 v11, v28, v29, vcc
	v_bitop3_b32 v74, v11, s93, v13 bitop3:0xde
	v_cmp_lt_i32_e32 vcc, -1, v24
	v_and_b32_e32 v13, 0xffffff00, v24
	v_pk_add_f32 v[24:25], v[22:23], v[8:9] op_sel_hi:[0,1]
	v_cndmask_b32_e32 v11, v28, v29, vcc
	v_cmp_lt_i32_e32 vcc, -1, v25
	v_bitop3_b32 v75, v11, s94, v13 bitop3:0xde
	v_and_b32_e32 v13, 0xffffff00, v25
	v_cndmask_b32_e32 v11, v28, v29, vcc
	v_cmp_lt_i32_e32 vcc, -1, v24
	v_bitop3_b32 v76, v11, s95, v13 bitop3:0xde
	v_and_b32_e32 v13, 0xffffff00, v24
	v_cndmask_b32_e32 v11, v28, v29, vcc
	v_bitop3_b32 v77, v11, s96, v13 bitop3:0xde
	v_mov_b32_e32 v13, v22
	v_mov_b32_e32 v20, v7
	v_pk_add_f32 v[20:21], v[12:13], v[20:21]
	s_movk_i32 s0, 0x7f
	v_cmp_lt_i32_e32 vcc, -1, v21
	v_and_b32_e32 v13, 0xffffff00, v21
	v_mov_b32_e32 v21, v6
	v_cndmask_b32_e32 v11, v28, v29, vcc
	v_bitop3_b32 v22, v11, s97, v13 bitop3:0xde
	v_cmp_lt_i32_e32 vcc, -1, v20
	v_and_b32_e32 v13, 0xffffff00, v20
	v_mov_b32_e32 v20, v9
	v_pk_add_f32 v[24:25], v[12:13], v[20:21] op_sel_hi:[0,1]
	v_cndmask_b32_e32 v11, v28, v29, vcc
	v_cmp_lt_i32_e32 vcc, -1, v25
	v_bitop3_b32 v78, v11, s4, v13 bitop3:0xde
	v_and_b32_e32 v11, 0xffffff00, v25
	v_cndmask_b32_e32 v9, v28, v29, vcc
	v_cmp_lt_i32_e32 vcc, -1, v24
	v_bitop3_b32 v25, v9, s5, v11 bitop3:0xde
	v_and_b32_e32 v11, 0xffffff00, v24
	v_cndmask_b32_e32 v9, v28, v29, vcc
	v_bitop3_b32 v24, v9, s80, v11 bitop3:0xde
	v_mov_b32_e32 v11, v12
	v_mov_b32_e32 v12, v7
	v_mov_b32_e32 v13, v8
	v_pk_add_f32 v[8:9], v[10:11], v[12:13]
	s_nop 0
	v_cmp_lt_i32_e32 vcc, -1, v9
	v_and_b32_e32 v9, 0xffffff00, v9
	s_nop 0
	v_cndmask_b32_e32 v11, v28, v29, vcc
	v_cmp_lt_i32_e32 vcc, -1, v8
	v_bitop3_b32 v12, v11, s81, v9 bitop3:0xde
	v_and_b32_e32 v8, 0xffffff00, v8
	v_cndmask_b32_e32 v9, v28, v29, vcc
	v_bitop3_b32 v13, v9, s22, v8 bitop3:0xde
; DI unsigned candkey(float s, int pos) { const unsigned b = __float_as_uint(s); const unsigned o = (b >> 31) ? ~b : (b ^ 0x80000000u); return (o & 0xffffff00u) | (unsigned)(255 - pos); }
; DI void phase10(const Params& P, char* smem) {
;     ...
;     C2[0] = candkey(v1[3] + v2[3], 51);
;     C2[1] = candkey(v1[4] + v2[0], 64);
;     C2[2] = candkey(v1[4] + v2[1], 65);
;     C2[3] = candkey(v1[4] + v2[2], 66);
;     C2[4] = candkey(v1[5] + v2[0], 80);
;     C2[5] = candkey(v1[5] + v2[1], 81);
;     C2[6] = candkey(v1[6] + v2[0], 96);
;     C2[7] = candkey(v1[6] + v2[1], 97);
;     C2[8] = candkey(v1[7] + v2[0], 112);
;     C2[9] = candkey(v1[7] + v2[1], 113);
;     C2[10] = candkey(v1[8] + v2[0], 128);
;     C2[11] = candkey(v1[9] + v2[0], 144);
;     C2[12] = candkey(v1[10] + v2[0], 160);
;     C2[13] = candkey(v1[11] + v2[0], 176);
;     C2[14] = candkey(v1[12] + v2[0], 192);
;     C2[15] = candkey(v1[13] + v2[0], 208);
;     C3[0] = candkey(v1[14] + v2[0], 224);
;     C3[1] = candkey(v1[15] + v2[0], 240);
;     C3[2] = 0u;
;     C3[3] = 0u;
;     C3[4] = 0u;
;     C3[5] = 0u;
;     C3[6] = 0u;
;     C3[7] = 0u;
;     C3[8] = 0u;
;     C3[9] = 0u;
;     C3[10] = 0u;
;     C3[11] = 0u;
;     C3[12] = 0u;
;     C3[13] = 0u;
;     C3[14] = 0u;
;     C3[15] = 0u;
;     SORT16(C1) SORT16(C2) SORT16(C3)
	v_pk_add_f32 v[8:9], v[10:11], v[20:21] op_sel_hi:[0,1]
	v_cmp_lt_i32_e32 vcc, -1, v9
	v_and_b32_e32 v9, 0xffffff00, v9
	v_xor_b32_sdwa v11, v33, v27 dst_sel:DWORD dst_unused:UNUSED_PAD src0_sel:WORD_1 src1_sel:DWORD
	v_cndmask_b32_e32 v10, v28, v29, vcc
	v_cmp_lt_i32_e32 vcc, -1, v8
	v_bitop3_b32 v20, v10, s23, v9 bitop3:0xde
	v_and_b32_e32 v8, 0xffffff00, v8
	v_cndmask_b32_e32 v9, v28, v29, vcc
	v_bitop3_b32 v21, v9, s82, v8 bitop3:0xde
	v_pk_add_f32 v[8:9], v[14:15], v[6:7] op_sel_hi:[0,1]
	v_cmp_lt_i32_e32 vcc, -1, v9
	v_and_b32_e32 v9, 0xffffff00, v9
	v_max_u32_e32 v84, v12, v13
	v_cndmask_b32_e32 v10, v28, v29, vcc
	v_cmp_lt_i32_e32 vcc, -1, v8
	v_bitop3_b32 v14, v10, s83, v9 bitop3:0xde
	v_and_b32_e32 v8, 0xffffff00, v8
	v_cndmask_b32_e32 v9, v28, v29, vcc
	v_bitop3_b32 v79, v9, s44, v8 bitop3:0xde
	v_pk_add_f32 v[8:9], v[16:17], v[6:7] op_sel_hi:[0,1]
	v_cmp_lt_i32_e32 vcc, -1, v9
	v_and_b32_e32 v9, 0xffffff00, v9
	v_min_u32_e32 v12, v12, v13
	v_cndmask_b32_e32 v10, v28, v29, vcc
	v_cmp_lt_i32_e32 vcc, -1, v8
	v_bitop3_b32 v16, v10, s45, v9 bitop3:0xde
	v_and_b32_e32 v8, 0xffffff00, v8
	v_cndmask_b32_e32 v9, v28, v29, vcc
	v_bitop3_b32 v80, v9, s33, v8 bitop3:0xde
	v_pk_add_f32 v[8:9], v[18:19], v[6:7] op_sel_hi:[0,1]
	v_cmp_lt_i32_e32 vcc, -1, v9
	v_and_b32_e32 v9, 0xffffff00, v9
	v_and_b32_sdwa v10, v32, s57 dst_sel:DWORD dst_unused:UNUSED_PAD src0_sel:WORD_1 src1_sel:DWORD
	v_cndmask_b32_e32 v6, v28, v29, vcc
	v_cmp_lt_i32_e32 vcc, -1, v8
	v_bitop3_b32 v18, v6, s87, v9 bitop3:0xde
	v_and_b32_sdwa v9, v33, s57 dst_sel:DWORD dst_unused:UNUSED_PAD src0_sel:WORD_1 src1_sel:DWORD
	v_cndmask_b32_e32 v6, v28, v29, vcc
	v_cmp_gt_i32_e32 vcc, 0, v33
	v_and_b32_e32 v8, 0xffffff00, v8
	v_xor_b32_sdwa v33, v30, v27 dst_sel:DWORD dst_unused:UNUSED_PAD src0_sel:WORD_1 src1_sel:DWORD
	v_cndmask_b32_e32 v9, v11, v9, vcc
	v_cmp_gt_i32_e32 vcc, 0, v32
	v_cvt_f32_f16_e32 v11, v9
	v_bitop3_b32 v32, v6, s2, v8 bitop3:0xde
	v_cndmask_b32_e32 v10, v81, v10, vcc
	v_cvt_f32_f16_e32 v10, v10
	v_mov_b32_e32 v6, v7
	v_max_u32_e32 v13, v20, v21
	v_min_u32_e32 v20, v20, v21
	v_pk_add_f32 v[8:9], v[6:7], v[10:11] op_sel_hi:[0,1]
	v_cmp_lt_i32_e32 vcc, -1, v9
	v_and_b32_e32 v9, 0xffffff00, v9
	v_xor_b32_sdwa v11, v31, v27 dst_sel:DWORD dst_unused:UNUSED_PAD src0_sel:WORD_1 src1_sel:DWORD
	v_cndmask_b32_e32 v7, v28, v29, vcc
	v_bitop3_b32 v7, v7, s0, v9 bitop3:0xde
	v_and_b32_sdwa v9, v31, s57 dst_sel:DWORD dst_unused:UNUSED_PAD src0_sel:WORD_1 src1_sel:DWORD
	v_cmp_gt_i32_e32 vcc, 0, v31
	v_and_b32_sdwa v10, v30, s57 dst_sel:DWORD dst_unused:UNUSED_PAD src0_sel:WORD_1 src1_sel:DWORD
	v_pk_add_f32 v[4:5], v[4:5], v[6:7] op_sel_hi:[1,0]
	v_cndmask_b32_e32 v9, v11, v9, vcc
	v_cmp_gt_i32_e32 vcc, 0, v30
	v_cvt_f32_f16_e32 v11, v9
	v_max_u32_e32 v21, v14, v79
	v_cndmask_b32_e32 v10, v33, v10, vcc
	v_cvt_f32_f16_e32 v10, v10
	v_cmp_lt_i32_e32 vcc, -1, v8
	v_and_b32_e32 v8, 0xffffff00, v8
	v_xor_b32_sdwa v33, v1, v27 dst_sel:DWORD dst_unused:UNUSED_PAD src0_sel:WORD_1 src1_sel:DWORD
	v_cndmask_b32_e32 v9, v28, v29, vcc
	v_bitop3_b32 v30, v9, s88, v8 bitop3:0xde
	v_pk_add_f32 v[8:9], v[6:7], v[10:11] op_sel_hi:[0,1]
	v_cmp_lt_i32_e32 vcc, -1, v9
	v_and_b32_e32 v9, 0xffffff00, v9
	v_xor_b32_sdwa v11, v3, v27 dst_sel:DWORD dst_unused:UNUSED_PAD src0_sel:WORD_1 src1_sel:DWORD
	v_cndmask_b32_e32 v10, v28, v29, vcc
	v_bitop3_b32 v31, v10, s89, v9 bitop3:0xde
	v_and_b32_sdwa v9, v3, s57 dst_sel:DWORD dst_unused:UNUSED_PAD src0_sel:WORD_1 src1_sel:DWORD
	v_cmp_gt_i32_e32 vcc, 0, v3
	v_and_b32_sdwa v10, v1, s57 dst_sel:DWORD dst_unused:UNUSED_PAD src0_sel:WORD_1 src1_sel:DWORD
	v_min_u32_e32 v14, v14, v79
	v_cndmask_b32_e32 v3, v11, v9, vcc
	v_cmp_gt_i32_e32 vcc, 0, v1
	v_cvt_f32_f16_e32 v11, v3
	v_and_b32_e32 v3, 0xffffff00, v8
	v_cndmask_b32_e32 v1, v33, v10, vcc
	v_cvt_f32_f16_e32 v10, v1
	v_cmp_lt_i32_e32 vcc, -1, v8
	v_max_u32_e32 v33, v67, v66
	v_min_u32_e32 v66, v67, v66
	v_pk_add_f32 v[8:9], v[6:7], v[10:11] op_sel_hi:[0,1]
	v_cndmask_b32_e32 v1, v28, v29, vcc
	v_cmp_lt_i32_e32 vcc, -1, v9
	v_bitop3_b32 v1, v1, s90, v3 bitop3:0xde
	v_and_b32_e32 v9, 0xffffff00, v9
	v_cndmask_b32_e32 v3, v28, v29, vcc
	v_cmp_lt_i32_e32 vcc, -1, v8
	v_bitop3_b32 v3, v3, 63, v9 bitop3:0xde
	v_and_b32_e32 v8, 0xffffff00, v8
	v_cndmask_b32_e32 v9, v28, v29, vcc
	v_cmp_lt_i32_e32 vcc, -1, v5
	v_and_b32_e32 v5, 0xffffff00, v5
	v_bitop3_b32 v8, v9, 47, v8 bitop3:0xde
	v_cndmask_b32_e32 v6, v28, v29, vcc
	v_cmp_lt_i32_e32 vcc, -1, v4
	v_bitop3_b32 v5, v6, 31, v5 bitop3:0xde
	v_and_b32_e32 v4, 0xffffff00, v4
	v_cndmask_b32_e32 v6, v28, v29, vcc
	v_bitop3_b32 v4, v6, 15, v4 bitop3:0xde
	v_max_u32_e32 v6, v69, v70
	v_min_u32_e32 v9, v69, v70
	v_max_u32_e32 v10, v71, v72
	v_min_u32_e32 v11, v71, v72
	v_max_u32_e32 v67, v64, v73
	v_min_u32_e32 v64, v64, v73
	v_max_u32_e32 v69, v74, v75
	v_min_u32_e32 v70, v74, v75
	v_max_u32_e32 v71, v76, v77
	v_min_u32_e32 v72, v76, v77
	v_max_u32_e32 v73, v22, v78
	v_min_u32_e32 v22, v22, v78
	v_max_u32_e32 v74, v25, v24
	v_min_u32_e32 v24, v25, v24
	v_max_u32_e32 v25, v6, v10
	v_min_u32_e32 v6, v6, v10
	v_max_u32_e32 v10, v9, v11
	v_min_u32_e32 v9, v9, v11
	v_max_u32_e32 v11, v33, v67
	v_min_u32_e32 v33, v33, v67
	v_max_u32_e32 v67, v66, v64
	v_min_u32_e32 v64, v66, v64
	v_max_u32_e32 v66, v69, v71
	v_min_u32_e32 v69, v69, v71
	v_max_u32_e32 v71, v70, v72
	v_min_u32_e32 v70, v70, v72
	v_max_u32_e32 v72, v73, v74
	v_min_u32_e32 v73, v73, v74
	v_max_u32_e32 v74, v22, v24
	v_min_u32_e32 v22, v22, v24
	v_max_u32_e32 v24, v10, v6
	v_min_u32_e32 v6, v10, v6
	v_max_u32_e32 v10, v67, v33
	v_min_u32_e32 v33, v67, v33
	v_max_u32_e32 v67, v71, v69
	v_min_u32_e32 v69, v71, v69
; DI void phase10(const Params& P, char* smem) {
;     ...
;     SORT16(C1) SORT16(C2) SORT16(C3)
;     MERGE16(C0, C1) MERGE16(C0, C2) MERGE16(C0, C3)
	v_max_u32_e32 v71, v74, v73
	v_min_u32_e32 v73, v74, v73
	v_max_u32_e32 v74, v25, v11
	v_min_u32_e32 v11, v25, v11
	v_max_u32_e32 v25, v24, v10
	v_min_u32_e32 v10, v24, v10
	v_max_u32_e32 v24, v6, v33
	v_min_u32_e32 v6, v6, v33
	v_max_u32_e32 v33, v9, v64
	v_min_u32_e32 v9, v9, v64
	v_max_u32_e32 v64, v66, v72
	v_min_u32_e32 v66, v66, v72
	v_max_u32_e32 v72, v67, v71
	v_min_u32_e32 v67, v67, v71
	v_max_u32_e32 v71, v69, v73
	v_min_u32_e32 v69, v69, v73
	v_max_u32_e32 v73, v70, v22
	v_min_u32_e32 v22, v70, v22
	v_max_u32_e32 v70, v24, v11
	v_min_u32_e32 v11, v24, v11
	v_max_u32_e32 v24, v33, v10
	v_min_u32_e32 v10, v33, v10
	v_max_u32_e32 v33, v71, v66
	v_min_u32_e32 v66, v71, v66
	v_max_u32_e32 v71, v73, v67
	v_min_u32_e32 v67, v73, v67
	v_max_u32_e32 v73, v25, v70
	v_min_u32_e32 v25, v25, v70
	v_max_u32_e32 v70, v24, v11
	v_min_u32_e32 v11, v24, v11
	v_max_u32_e32 v24, v10, v6
	v_min_u32_e32 v6, v10, v6
	v_max_u32_e32 v10, v72, v33
	v_min_u32_e32 v33, v72, v33
	v_max_u32_e32 v72, v71, v66
	v_min_u32_e32 v66, v71, v66
	v_max_u32_e32 v71, v67, v69
	v_min_u32_e32 v67, v67, v69
	v_max_u32_e32 v79, v16, v80
	v_min_u32_e32 v16, v16, v80
	v_max_u32_e32 v80, v18, v32
	v_min_u32_e32 v18, v18, v32
	v_max_u32_e32 v32, v7, v30
	v_min_u32_e32 v7, v7, v30
	v_max_u32_e32 v30, v31, v1
	v_min_u32_e32 v1, v31, v1
	v_max_u32_e32 v31, v3, v8
	v_min_u32_e32 v3, v3, v8
	v_min_u32_e32 v69, v74, v64
	v_max_u32_e32 v75, v73, v10
	v_min_u32_e32 v10, v73, v10
	v_max_u32_e32 v73, v25, v33
	v_min_u32_e32 v25, v25, v33
	v_max_u32_e32 v33, v70, v72
	v_min_u32_e32 v70, v70, v72
	v_max_u32_e32 v72, v11, v66
	v_min_u32_e32 v11, v11, v66
	v_max_u32_e32 v66, v24, v71
	v_min_u32_e32 v24, v24, v71
	v_max_u32_e32 v71, v6, v67
	v_min_u32_e32 v6, v6, v67
	v_max_u32_e32 v67, v9, v22
	v_max_u32_e32 v8, v84, v13
	v_min_u32_e32 v13, v84, v13
	v_max_u32_e32 v84, v12, v20
	v_min_u32_e32 v12, v12, v20
	v_max_u32_e32 v20, v21, v79
	v_min_u32_e32 v21, v21, v79
	v_max_u32_e32 v79, v14, v16
	v_min_u32_e32 v14, v14, v16
	v_max_u32_e32 v16, v80, v32
	v_min_u32_e32 v32, v80, v32
	v_max_u32_e32 v80, v18, v7
	v_min_u32_e32 v7, v18, v7
	v_max_u32_e32 v18, v30, v31
	v_min_u32_e32 v30, v30, v31
	v_max_u32_e32 v31, v1, v3
	v_min_u32_e32 v9, v9, v22
	v_max_u32_e32 v22, v72, v69
	v_min_u32_e32 v69, v72, v69
	v_max_u32_e32 v72, v66, v10
	v_min_u32_e32 v10, v66, v10
	v_max_u32_e32 v66, v71, v25
	v_min_u32_e32 v25, v71, v25
	v_max_u32_e32 v71, v67, v70
	v_min_u32_e32 v67, v67, v70
	v_min_u32_e32 v1, v1, v3
	v_max_u32_e32 v3, v84, v13
	v_min_u32_e32 v13, v84, v13
	v_max_u32_e32 v84, v79, v21
	v_min_u32_e32 v21, v79, v21
	v_max_u32_e32 v79, v80, v32
	v_min_u32_e32 v32, v80, v32
	v_max_u32_e32 v80, v31, v30
	v_min_u32_e32 v30, v31, v30
	v_max_u32_e32 v70, v73, v22
	v_min_u32_e32 v22, v73, v22
	v_max_u32_e32 v73, v33, v72
	v_min_u32_e32 v33, v33, v72
	v_max_u32_e32 v72, v66, v69
	v_min_u32_e32 v66, v66, v69
	v_max_u32_e32 v69, v71, v10
	v_min_u32_e32 v10, v71, v10
	v_max_u32_e32 v71, v25, v11
	v_min_u32_e32 v11, v25, v11
	v_max_u32_e32 v25, v67, v24
	v_min_u32_e32 v24, v67, v24
	v_max_u32_e32 v31, v8, v20
	v_min_u32_e32 v8, v8, v20
	v_max_u32_e32 v20, v3, v84
	v_min_u32_e32 v3, v3, v84
	v_max_u32_e32 v84, v13, v21
	v_min_u32_e32 v13, v13, v21
	v_max_u32_e32 v21, v12, v14
	v_min_u32_e32 v12, v12, v14
	v_max_u32_e32 v14, v16, v18
	v_min_u32_e32 v16, v16, v18
	v_max_u32_e32 v18, v79, v80
	v_min_u32_e32 v79, v79, v80
	v_max_u32_e32 v80, v32, v30
	v_min_u32_e32 v30, v32, v30
	v_max_u32_e32 v32, v7, v1
	v_min_u32_e32 v67, v75, v70
	v_min_u32_e32 v76, v73, v22
	v_min_u32_e32 v77, v33, v72
	v_min_u32_e32 v78, v69, v66
	v_min_u32_e32 v81, v10, v71
	v_min_u32_e32 v82, v25, v11
	v_min_u32_e32 v83, v24, v6
	v_min_u32_e32 v1, v7, v1
	v_max_u32_e32 v7, v84, v8
	v_min_u32_e32 v8, v84, v8
	v_max_u32_e32 v84, v21, v3
	v_min_u32_e32 v3, v21, v3
	v_max_u32_e32 v21, v80, v16
	v_min_u32_e32 v16, v80, v16
	v_max_u32_e32 v80, v32, v79
	v_min_u32_e32 v32, v32, v79
	v_max_u32_e32 v79, v20, v7
	v_min_u32_e32 v7, v20, v7
	v_max_u32_e32 v20, v84, v8
	v_min_u32_e32 v8, v84, v8
	v_max_u32_e32 v84, v3, v13
	v_min_u32_e32 v3, v3, v13
	v_max_u32_e32 v13, v18, v21
	v_min_u32_e32 v18, v18, v21
	v_max_u32_e32 v21, v80, v16
	v_min_u32_e32 v16, v80, v16
	v_max_u32_e32 v80, v32, v30
	v_min_u32_e32 v30, v32, v30
	v_max_u32_e32 v9, v35, v9
	v_max_u32_e32 v35, v36, v83
	v_max3_u32 v6, v37, v24, v6
	v_max_u32_e32 v24, v38, v82
	v_max3_u32 v11, v39, v25, v11
	v_max_u32_e32 v25, v40, v81
	v_max3_u32 v10, v41, v10, v71
	v_max_u32_e32 v36, v57, v78
	v_max3_u32 v37, v58, v69, v66
	v_max_u32_e32 v38, v59, v77
	v_max3_u32 v33, v60, v33, v72
	v_max_u32_e32 v39, v61, v76
	v_max3_u32 v22, v62, v73, v22
	v_max_u32_e32 v40, v63, v67
	v_max3_u32 v41, v65, v75, v70
	v_max3_u32 v57, v68, v74, v64
	v_min_u32_e32 v32, v31, v14
	v_max_u32_e32 v85, v79, v13
	v_min_u32_e32 v13, v79, v13
	v_max_u32_e32 v79, v7, v18
	v_min_u32_e32 v7, v7, v18
	v_max_u32_e32 v18, v20, v21
	v_min_u32_e32 v20, v20, v21
	v_max_u32_e32 v21, v8, v16
	v_min_u32_e32 v8, v8, v16
	v_max_u32_e32 v16, v84, v80
	v_min_u32_e32 v80, v84, v80
	v_max_u32_e32 v84, v3, v30
	v_min_u32_e32 v3, v3, v30
	v_max_u32_e32 v30, v12, v1
	v_max_u32_e32 v58, v9, v37
	v_min_u32_e32 v9, v9, v37
	v_max_u32_e32 v37, v35, v38
	v_min_u32_e32 v35, v35, v38
	v_max_u32_e32 v38, v6, v33
	v_min_u32_e32 v6, v6, v33
	v_max_u32_e32 v33, v24, v39
	v_min_u32_e32 v24, v24, v39
	v_max_u32_e32 v39, v11, v22
	v_min_u32_e32 v11, v11, v22
	v_max_u32_e32 v22, v25, v40
; DI unsigned lut4(const unsigned (&W)[4], int a) { const int j = a >> 2; const unsigned w = j == 0 ? W[0] : (j == 1 ? W[1] : (j == 2 ? W[2] : W[3])); return (w >> ((a & 3) * 8)) & 0xffu; }
; DI void phase10(const Params& P, char* smem) {
;     ...
;     SORT16(C1) SORT16(C2) SORT16(C3)
;     MERGE16(C0, C1) MERGE16(C0, C2) MERGE16(C0, C3)
;     float e[16]; int te[16]; float sum = 0.f;
;     const float tv0 = [&]() { const unsigned o = C0[0] & 0xffffff00u; return __uint_as_float((o >> 31) ? (o ^ 0x80000000u) : ~o); }();
; #pragma unroll
;     for (int k = 0; k < 16; ++k) {
;       const unsigned key = C0[k]; const unsigned o = key & 0xffffff00u;
;       const float val = __uint_as_float((o >> 31) ? (o ^ 0x80000000u) : ~o);
;       const int pos = 255 - (int)(key & 255u);
;       te[k] = (int)(lut4(W1, pos >> 4) * 128u + lut4(W2, pos & 15));
	v_min_u32_e32 v25, v25, v40
	v_max_u32_e32 v40, v10, v41
	v_min_u32_e32 v10, v10, v41
	v_max_u32_e32 v41, v36, v57
	v_min_u32_e32 v36, v36, v57
	v_min_u32_e32 v1, v12, v1
	v_max_u32_e32 v12, v21, v32
	v_min_u32_e32 v21, v21, v32
	v_max_u32_e32 v32, v16, v13
	v_min_u32_e32 v13, v16, v13
	v_max_u32_e32 v16, v84, v7
	v_min_u32_e32 v7, v84, v7
	v_max_u32_e32 v84, v30, v20
	v_min_u32_e32 v20, v30, v20
	v_max_u32_e32 v57, v58, v39
	v_min_u32_e32 v39, v58, v39
	v_max_u32_e32 v58, v37, v22
	v_min_u32_e32 v22, v37, v22
	v_max_u32_e32 v37, v38, v40
	v_min_u32_e32 v38, v38, v40
	v_max_u32_e32 v40, v33, v41
	v_min_u32_e32 v33, v33, v41
	v_max_u32_e32 v41, v9, v11
	v_min_u32_e32 v9, v9, v11
	v_max_u32_e32 v11, v35, v25
	v_min_u32_e32 v25, v35, v25
	v_max_u32_e32 v35, v6, v10
	v_min_u32_e32 v6, v6, v10
	v_max_u32_e32 v10, v24, v36
	v_min_u32_e32 v24, v24, v36
	v_max_u32_e32 v30, v79, v12
	v_min_u32_e32 v12, v79, v12
	v_max_u32_e32 v79, v18, v32
	v_min_u32_e32 v18, v18, v32
	v_max_u32_e32 v32, v16, v21
	v_min_u32_e32 v16, v16, v21
	v_max_u32_e32 v21, v84, v13
	v_min_u32_e32 v13, v84, v13
	v_max_u32_e32 v84, v7, v8
	v_min_u32_e32 v7, v7, v8
	v_max_u32_e32 v8, v20, v80
	v_min_u32_e32 v20, v20, v80
	v_max_u32_e32 v36, v57, v37
	v_min_u32_e32 v37, v57, v37
	v_max_u32_e32 v57, v58, v40
	v_min_u32_e32 v40, v58, v40
	v_max_u32_e32 v58, v39, v38
	v_min_u32_e32 v38, v39, v38
	v_max_u32_e32 v39, v22, v33
	v_min_u32_e32 v22, v22, v33
	v_max_u32_e32 v33, v41, v35
	v_min_u32_e32 v35, v41, v35
	v_max_u32_e32 v41, v11, v10
	v_min_u32_e32 v10, v11, v10
	v_max_u32_e32 v11, v9, v6
	v_min_u32_e32 v6, v9, v6
	v_max_u32_e32 v9, v25, v24
	v_min_u32_e32 v24, v25, v24
	v_max_u32_e32 v80, v85, v30
	v_min_u32_e32 v30, v85, v30
	v_max_u32_e32 v85, v79, v12
	v_min_u32_e32 v12, v79, v12
	v_max_u32_e32 v79, v18, v32
	v_min_u32_e32 v18, v18, v32
	v_max_u32_e32 v32, v21, v16
	v_min_u32_e32 v16, v21, v16
	v_max_u32_e32 v21, v13, v84
	v_min_u32_e32 v13, v13, v84
	v_max_u32_e32 v84, v8, v7
	v_min_u32_e32 v7, v8, v7
	v_max_u32_e32 v8, v20, v3
	v_min_u32_e32 v3, v20, v3
	v_min_u32_e32 v25, v36, v57
	v_min_u32_e32 v59, v37, v40
	v_min_u32_e32 v60, v58, v39
	v_min_u32_e32 v61, v38, v22
	v_min_u32_e32 v62, v33, v41
	v_min_u32_e32 v63, v35, v10
	v_min_u32_e32 v64, v11, v9
	v_min_u32_e32 v65, v6, v24
	v_max3_u32 v1, v36, v57, v1
	v_max_u32_e32 v3, v25, v3
	v_max3_u32 v8, v37, v40, v8
	v_max_u32_e32 v7, v59, v7
	v_max3_u32 v25, v58, v39, v84
	v_max_u32_e32 v13, v60, v13
	v_max3_u32 v21, v38, v22, v21
	v_max_u32_e32 v16, v61, v16
	v_max3_u32 v22, v33, v41, v32
	v_max_u32_e32 v18, v62, v18
	v_max3_u32 v10, v35, v10, v79
	v_max_u32_e32 v12, v63, v12
	v_max3_u32 v9, v11, v9, v85
	v_max_u32_e32 v11, v64, v30
	v_max3_u32 v6, v6, v24, v80
	v_max3_u32 v14, v65, v31, v14
	v_max_u32_e32 v24, v1, v22
	v_min_u32_e32 v1, v1, v22
	v_max_u32_e32 v22, v3, v18
	v_min_u32_e32 v3, v3, v18
	v_max_u32_e32 v18, v8, v10
	v_min_u32_e32 v8, v8, v10
	v_max_u32_e32 v10, v7, v12
	v_min_u32_e32 v7, v7, v12
	v_max_u32_e32 v12, v25, v9
	v_min_u32_e32 v9, v25, v9
	v_max_u32_e32 v25, v13, v11
	v_min_u32_e32 v11, v13, v11
	v_max_u32_e32 v13, v21, v6
	v_min_u32_e32 v6, v21, v6
	v_max_u32_e32 v21, v16, v14
	v_min_u32_e32 v14, v16, v14
	v_max_u32_e32 v16, v24, v12
	v_min_u32_e32 v12, v24, v12
	v_max_u32_e32 v24, v22, v25
	v_min_u32_e32 v22, v22, v25
	v_max_u32_e32 v25, v18, v13
	v_min_u32_e32 v13, v18, v13
	v_max_u32_e32 v18, v10, v21
	v_min_u32_e32 v10, v10, v21
	v_max_u32_e32 v21, v1, v9
	v_min_u32_e32 v1, v1, v9
	v_max_u32_e32 v9, v3, v11
	v_min_u32_e32 v3, v3, v11
	v_max_u32_e32 v11, v8, v6
	v_min_u32_e32 v6, v8, v6
	v_max_u32_e32 v8, v7, v14
	v_min_u32_e32 v7, v7, v14
	v_max_u32_e32 v14, v16, v25
	v_min_u32_e32 v16, v16, v25
	v_max_u32_e32 v25, v24, v18
	v_min_u32_e32 v18, v24, v18
	v_max_u32_e32 v24, v12, v13
	v_min_u32_e32 v12, v12, v13
	v_max_u32_e32 v13, v22, v10
	v_min_u32_e32 v10, v22, v10
	v_max_u32_e32 v22, v21, v11
	v_min_u32_e32 v11, v21, v11
	v_max_u32_e32 v21, v9, v8
	v_min_u32_e32 v8, v9, v8
	v_max_u32_e32 v9, v1, v6
	v_min_u32_e32 v1, v1, v6
	v_max_u32_e32 v6, v3, v7
	v_min_u32_e32 v3, v3, v7
	v_min_u32_e32 v20, v5, v4
	v_max_u32_e32 v69, v9, v6
	v_min_u32_e32 v70, v9, v6
	v_min_u32_e32 v6, v1, v3
	v_max_u32_e32 v57, v14, v25
	v_min_u32_e32 v58, v14, v25
	v_max_u32_e32 v59, v16, v18
	v_min_u32_e32 v60, v16, v18
	v_max_u32_e32 v61, v24, v13
	v_min_u32_e32 v62, v24, v13
	v_max_u32_e32 v63, v12, v10
	v_min_u32_e32 v64, v12, v10
	v_max_u32_e32 v65, v22, v21
	v_min_u32_e32 v66, v22, v21
	v_max_u32_e32 v67, v11, v8
	v_min_u32_e32 v68, v11, v8
	v_max3_u32 v71, v1, v3, v20
	v_max3_u32 v72, v6, v5, v4
	v_max_u32_e32 v11, v57, v65
	v_max_u32_e32 v12, v58, v66
	v_max_u32_e32 v13, v59, v67
	v_max_u32_e32 v32, v60, v68
	v_max_u32_e32 v33, v61, v69
	v_max_u32_e32 v35, v62, v70
	v_max_u32_e32 v36, v63, v71
	v_max_u32_e32 v37, v64, v72
	v_max_u32_e32 v9, v11, v33
	v_max_u32_e32 v10, v12, v35
	v_max_u32_e32 v22, v13, v36
	v_max_u32_e32 v24, v32, v37
	v_max_u32_e32 v8, v9, v22
	v_max_u32_e32 v18, v10, v24
	v_max_u32_e32 v4, v8, v18
	v_bitop3_b32 v1, v4, s3, v4 bitop3:0xc
	v_cmp_lt_u32_e32 vcc, 63, v1
	v_mov_b32_e32 v3, v15
	s_and_saveexec_b64 s[0:1], vcc
	s_cbranch_execz .LBB0_1193
	v_lshrrev_b32_e32 v5, 6, v1
	v_cmp_lt_i32_e32 vcc, 1, v5
	s_mov_b64 s[6:7], 0
	s_and_saveexec_b64 s[8:9], vcc
	s_xor_b64 s[8:9], exec, s[8:9]
	s_cbranch_execnz .LBB0_1381
	s_or_saveexec_b64 s[8:9], s[8:9]
	v_mov_b32_e32 v3, v19
	s_xor_b64 exec, exec, s[8:9]
	s_cbranch_execnz .LBB0_1384
